# adds: XOR-swizzled LDS tile in the V-transpose units (ds_read_u16 8-way bank conflicts removed)
# speedup vs baseline: 1.0029x; 1.0029x over previous
; DI void phase_prep(KP p, int l, char* ldsc) {
;     ...
;       bf16_t* Tt = (bf16_t*)ldsc;
;       __syncthreads();
; #pragma unroll
;       for (int uu = 0; uu < 4; ++uu) {
;         const int q = tid + NT * uu, rr = q >> 5, pc = q & 31;
;         *(u32x4*)(Tt + rr * 264 + pc * 8) = *(const u32x4*)(p->P + (size_t)(row0 + rr) * INC + colbase + pc * 8);
;       }
;       __syncthreads();
; #pragma unroll
;       for (int uu = 0; uu < 4; ++uu) {
;         const int q = tid + NT * uu, c = q >> 3, pk = q & 7;
;         const bf16_t* s = Tt + (8 * pk) * 264 + c;
;         u32x4 o;
;         o.x = (unsigned)s[0] | ((unsigned)s[264] << 16); o.y = (unsigned)s[2 * 264] | ((unsigned)s[3 * 264] << 16);
;         o.z = (unsigned)s[4 * 264] | ((unsigned)s[5 * 264] << 16); o.w = (unsigned)s[6 * 264] | ((unsigned)s[7 * 264] << 16);
.LBB0_399:
	s_cmpk_gt_u32 s0, 0x317
	s_cbranch_scc1 .LBB0_410
	v_lshlrev_b32_e32 v2, 3, v42
	v_add_u32_e32 v6, 0x200, v42
	v_add_u32_e32 v8, 0x400, v42
	v_add_u32_e32 v10, 0x600, v42
	v_and_b32_e32 v0, 0xf8, v2
	v_and_b32_e32 v2, 56, v2
	s_movk_i32 s1, 0x210
	v_ashrrev_i32_e32 v12, 5, v42
	v_ashrrev_i32_e32 v13, 5, v6
	v_ashrrev_i32_e32 v14, 5, v8
	v_ashrrev_i32_e32 v15, 5, v10
	v_lshl_add_u32 v3, v0, 1, 0
	v_mad_u32_u24 v4, v2, s1, 0
	v_mul_lo_u32 v5, v12, s1
	v_mul_lo_u32 v7, v13, s1
	v_mul_lo_u32 v9, v14, s1
	v_mul_lo_u32 v11, v15, s1
	v_ashrrev_i32_e32 v16, 3, v42
	v_ashrrev_i32_e32 v18, 3, v6
	v_ashrrev_i32_e32 v20, 3, v8
	v_ashrrev_i32_e32 v22, 3, v10
	v_lshl_add_u32 v17, v16, 1, v4
	v_lshl_add_u32 v19, v18, 1, v4
	v_lshl_add_u32 v21, v20, 1, v4
	v_lshl_add_u32 v23, v22, 1, v4
	v_lshlrev_b32_e32 v0, 1, v0
	v_add_u32_e32 v24, v3, v5
	v_add_u32_e32 v25, v3, v7
	v_add_u32_e32 v26, v3, v9
	v_add_u32_e32 v27, v3, v11
	v_bfe_u32 v244, v12, 3, 3
	v_lshlrev_b32_e32 v244, 4, v244
	v_xor_b32_e32 v244, v3, v244
	v_add_u32_e32 v24, v244, v5
	v_bfe_u32 v244, v13, 3, 3
	v_lshlrev_b32_e32 v244, 4, v244
	v_xor_b32_e32 v244, v3, v244
	v_add_u32_e32 v25, v244, v7
	v_bfe_u32 v244, v14, 3, 3
	v_lshlrev_b32_e32 v244, 4, v244
	v_xor_b32_e32 v244, v3, v244
	v_add_u32_e32 v26, v244, v9
	v_bfe_u32 v244, v15, 3, 3
	v_lshlrev_b32_e32 v244, 4, v244
	v_xor_b32_e32 v244, v3, v244
	v_add_u32_e32 v27, v244, v11
	v_lshrrev_b32_e32 v246, 3, v2
	v_lshrrev_b32_e32 v244, 3, v16
	v_xor_b32_e32 v244, v244, v246
	v_and_b32_e32 v245, 7, v16
	v_lshlrev_b32_e32 v244, 4, v244
	v_lshl_add_u32 v244, v245, 1, v244
	v_add_u32_e32 v17, v244, v4
	v_lshrrev_b32_e32 v244, 3, v18
	v_xor_b32_e32 v244, v244, v246
	v_and_b32_e32 v245, 7, v18
	v_lshlrev_b32_e32 v244, 4, v244
	v_lshl_add_u32 v244, v245, 1, v244
	v_add_u32_e32 v19, v244, v4
	v_lshrrev_b32_e32 v244, 3, v20
	v_xor_b32_e32 v244, v244, v246
	v_and_b32_e32 v245, 7, v20
	v_lshlrev_b32_e32 v244, 4, v244
	v_lshl_add_u32 v244, v245, 1, v244
	v_add_u32_e32 v21, v244, v4
	v_lshrrev_b32_e32 v244, 3, v22
	v_xor_b32_e32 v244, v244, v246
	v_and_b32_e32 v245, 7, v22
	v_lshlrev_b32_e32 v244, 4, v244
	v_lshl_add_u32 v244, v245, 1, v244
	v_add_u32_e32 v23, v244, v4
	v_lshlrev_b32_e32 v10, 1, v2
	s_branch .LBB0_403
